# GEMM unit headers: accumulator zeroing with v_mov_b64 (half the instructions) on three GEMM instances
# baseline (speedup 1.0000x reference)
; template <class Epi, class Sched, bool ALIGN_EPI = false, bool SP2 = false>
; __device__ __forceinline__ void gemm_phase(PG8_LAS unsigned char* lds, const Gemm g, const Sched& S, const Epi& E, const int tid) {
;     ...
; #pragma unroll
;         for (int a = 0; a < 2; ++a)
; #pragma unroll
;             for (int b = 0; b < 2; ++b)
; #pragma unroll
;                 for (int m = 0; m < 4; ++m)
; #pragma unroll
;                     for (int n = 0; n < 2; ++n) acc[a][b][m][n] = (f32x4){0.f, 0.f, 0.f, 0.f};
;         cur = nxt; cA = nA; cB = nB; ++ui;
.LBB0_142:
	v_mov_b32_e32 v123, 0
	s_andn2_b64 vcc, exec, s[56:57]
	v_mov_b32_e32 v122, v123
	v_mov_b32_e32 v121, v123
	v_mov_b32_e32 v120, v123
	v_mov_b32_e32 v127, v123
	v_mov_b32_e32 v126, v123
	v_mov_b32_e32 v125, v123
	v_mov_b32_e32 v124, v123
	v_mov_b32_e32 v111, v123
	v_mov_b32_e32 v110, v123
	v_mov_b32_e32 v109, v123
	v_mov_b32_e32 v108, v123
	v_mov_b32_e32 v107, v123
	v_mov_b32_e32 v106, v123
	v_mov_b32_e32 v105, v123
	v_mov_b32_e32 v104, v123
	v_mov_b32_e32 v95, v123
	v_mov_b32_e32 v94, v123
	v_mov_b32_e32 v93, v123
	v_mov_b32_e32 v92, v123
	v_mov_b32_e32 v91, v123
	v_mov_b32_e32 v90, v123
	v_mov_b32_e32 v89, v123
	v_mov_b32_e32 v88, v123
	v_mov_b32_e32 v79, v123
	v_mov_b32_e32 v78, v123
	v_mov_b32_e32 v77, v123
	v_mov_b32_e32 v76, v123
	v_mov_b32_e32 v75, v123
	v_mov_b32_e32 v74, v123
	v_mov_b32_e32 v73, v123
	v_mov_b32_e32 v72, v123
	v_mov_b32_e32 v119, v123
	v_mov_b32_e32 v118, v123
	v_mov_b32_e32 v117, v123
	v_mov_b32_e32 v116, v123
	v_mov_b32_e32 v115, v123
	v_mov_b32_e32 v114, v123
	v_mov_b32_e32 v113, v123
	v_mov_b32_e32 v112, v123
	v_mov_b32_e32 v103, v123
	v_mov_b32_e32 v102, v123
	v_mov_b32_e32 v101, v123
	v_mov_b32_e32 v100, v123
	v_mov_b32_e32 v99, v123
	v_mov_b32_e32 v98, v123
	v_mov_b32_e32 v97, v123
	v_mov_b32_e32 v96, v123
	v_mov_b32_e32 v87, v123
	v_mov_b32_e32 v86, v123
	v_mov_b32_e32 v85, v123
	v_mov_b32_e32 v84, v123
	v_mov_b32_e32 v83, v123
	v_mov_b32_e32 v82, v123
	v_mov_b32_e32 v81, v123
	v_mov_b32_e32 v80, v123
	v_mov_b32_e32 v71, v123
	v_mov_b32_e32 v70, v123
	v_mov_b32_e32 v69, v123
	v_mov_b32_e32 v68, v123
	v_mov_b32_e32 v67, v123
	v_mov_b32_e32 v66, v123
	v_mov_b32_e32 v65, v123
	v_mov_b32_e32 v64, v123
	v_mov_b32_e32 v63, v123
	v_mov_b32_e32 v62, v123
	v_mov_b32_e32 v61, v123
	v_mov_b32_e32 v60, v123
	v_mov_b32_e32 v59, v123
	v_mov_b32_e32 v58, v123
	v_mov_b32_e32 v57, v123
	v_mov_b32_e32 v56, v123
	v_mov_b32_e32 v47, v123
	v_mov_b32_e32 v46, v123
	v_mov_b32_e32 v45, v123
	v_mov_b32_e32 v44, v123
	v_mov_b32_e32 v43, v123
	v_mov_b32_e32 v42, v123
	v_mov_b32_e32 v41, v123
	v_mov_b32_e32 v40, v123
	v_mov_b32_e32 v31, v123
	v_mov_b32_e32 v30, v123
	v_mov_b32_e32 v29, v123
	v_mov_b32_e32 v28, v123
	v_mov_b32_e32 v27, v123
	v_mov_b32_e32 v26, v123
	v_mov_b32_e32 v25, v123
	v_mov_b32_e32 v24, v123
	v_mov_b32_e32 v15, v123
	v_mov_b32_e32 v14, v123
	v_mov_b32_e32 v13, v123
	v_mov_b32_e32 v12, v123
	v_mov_b32_e32 v11, v123
	v_mov_b32_e32 v10, v123
	v_mov_b32_e32 v9, v123
	v_mov_b32_e32 v8, v123
	v_mov_b32_e32 v55, v123
	v_mov_b32_e32 v54, v123
	v_mov_b32_e32 v53, v123
	v_mov_b32_e32 v52, v123
	v_mov_b32_e32 v51, v123
	v_mov_b32_e32 v50, v123
	v_mov_b32_e32 v49, v123
	v_mov_b32_e32 v48, v123
	v_mov_b32_e32 v39, v123
	v_mov_b32_e32 v38, v123
	v_mov_b32_e32 v37, v123
	v_mov_b32_e32 v36, v123
	v_mov_b32_e32 v35, v123
	v_mov_b32_e32 v34, v123
	v_mov_b32_e32 v33, v123
	v_mov_b32_e32 v32, v123
	v_mov_b32_e32 v23, v123
	v_mov_b32_e32 v22, v123
	v_mov_b32_e32 v21, v123
	v_mov_b32_e32 v20, v123
	v_mov_b32_e32 v19, v123
	v_mov_b32_e32 v18, v123
	v_mov_b32_e32 v17, v123
	v_mov_b32_e32 v16, v123
	v_mov_b32_e32 v7, v123
	v_mov_b32_e32 v6, v123
	v_mov_b32_e32 v5, v123
	v_mov_b32_e32 v4, v123
	v_mov_b32_e32 v3, v123
	v_mov_b32_e32 v2, v123
	v_mov_b32_e32 v1, v123
	v_mov_b32_e32 v0, v123
	s_cbranch_vccnz .LBB0_145
	s_add_u32 s0, s0, 0x80
	s_addc_u32 s1, s1, 0
	s_add_u32 s8, s66, 0x100
	v_mov_b32_e32 v0, 0
	s_addc_u32 s9, s67, 0
	s_mov_b32 s66, 0
	v_mov_b32_e32 v1, v0
	v_mov_b64_e32 v[2:3], v[0:1]
	v_mov_b64_e32 v[4:5], v[0:1]
	v_mov_b64_e32 v[6:7], v[0:1]
	v_mov_b64_e32 v[8:9], v[0:1]
	v_mov_b64_e32 v[10:11], v[0:1]
	v_mov_b64_e32 v[12:13], v[0:1]
	v_mov_b64_e32 v[14:15], v[0:1]
	v_mov_b64_e32 v[16:17], v[0:1]
	v_mov_b64_e32 v[18:19], v[0:1]
	v_mov_b64_e32 v[20:21], v[0:1]
	v_mov_b64_e32 v[22:23], v[0:1]
	v_mov_b64_e32 v[24:25], v[0:1]
	v_mov_b64_e32 v[26:27], v[0:1]
	v_mov_b64_e32 v[28:29], v[0:1]
	v_mov_b64_e32 v[30:31], v[0:1]
	v_mov_b64_e32 v[32:33], v[0:1]
	v_mov_b64_e32 v[34:35], v[0:1]
	v_mov_b64_e32 v[36:37], v[0:1]
	v_mov_b64_e32 v[38:39], v[0:1]
	v_mov_b64_e32 v[40:41], v[0:1]
	v_mov_b64_e32 v[42:43], v[0:1]
	v_mov_b64_e32 v[44:45], v[0:1]
	v_mov_b64_e32 v[46:47], v[0:1]
	v_mov_b64_e32 v[48:49], v[0:1]
	v_mov_b64_e32 v[50:51], v[0:1]
	v_mov_b64_e32 v[52:53], v[0:1]
	v_mov_b64_e32 v[54:55], v[0:1]
	v_mov_b64_e32 v[56:57], v[0:1]
	v_mov_b64_e32 v[58:59], v[0:1]
	v_mov_b64_e32 v[60:61], v[0:1]
	v_mov_b64_e32 v[62:63], v[0:1]
	v_mov_b64_e32 v[64:65], v[0:1]
	v_mov_b64_e32 v[66:67], v[0:1]
	v_mov_b64_e32 v[68:69], v[0:1]
	v_mov_b64_e32 v[70:71], v[0:1]
	v_mov_b64_e32 v[72:73], v[0:1]
	v_mov_b64_e32 v[74:75], v[0:1]
	v_mov_b64_e32 v[76:77], v[0:1]
	v_mov_b64_e32 v[78:79], v[0:1]
	v_mov_b64_e32 v[80:81], v[0:1]
	v_mov_b64_e32 v[82:83], v[0:1]
	v_mov_b64_e32 v[84:85], v[0:1]
	v_mov_b64_e32 v[86:87], v[0:1]
	v_mov_b64_e32 v[88:89], v[0:1]
	v_mov_b64_e32 v[90:91], v[0:1]
	v_mov_b64_e32 v[92:93], v[0:1]
	v_mov_b64_e32 v[94:95], v[0:1]
	v_mov_b64_e32 v[96:97], v[0:1]
	v_mov_b64_e32 v[98:99], v[0:1]
	v_mov_b64_e32 v[100:101], v[0:1]
	v_mov_b64_e32 v[102:103], v[0:1]
	v_mov_b64_e32 v[104:105], v[0:1]
	v_mov_b64_e32 v[106:107], v[0:1]
	v_mov_b64_e32 v[108:109], v[0:1]
	v_mov_b64_e32 v[110:111], v[0:1]
	v_mov_b64_e32 v[112:113], v[0:1]
	v_mov_b64_e32 v[114:115], v[0:1]
	v_mov_b64_e32 v[116:117], v[0:1]
	v_mov_b64_e32 v[118:119], v[0:1]
	v_mov_b64_e32 v[124:125], v[0:1]
	v_mov_b64_e32 v[126:127], v[0:1]
	v_mov_b32_e32 v120, v0
	v_mov_b32_e32 v121, v0
	v_mov_b32_e32 v122, v0
	v_mov_b32_e32 v123, v0

; template <class Epi, class Sched, bool ALIGN_EPI = false, bool SP2 = false>
; __device__ __forceinline__ void gemm_phase(PG8_LAS unsigned char* lds, const Gemm g, const Sched& S, const Epi& E, const int tid) {
;     ...
;         const bool has_next = S.next(ui + 1, nxt);
;         const char* nA = has_next ? (const char*)g.A + (size_t)nxt.pm * tstep : cA; const char* nB = has_next ? (const char*)g.Bt + (size_t)nxt.pn * tstep : cB;
;         for (int t = 0; t < nt; t += 2) {
;             const bool last = (t == nt - 2);
;             const char* a1 = cA + (size_t)(t + 1) * kstep;
;             const char* a2 = last ? nA : cA + (size_t)(t + 2) * kstep; const char* b2 = last ? nB : cB + (size_t)(t + 2) * kstep;
;     ...
; #pragma unroll
;         for (int a = 0; a < 2; ++a)
; #pragma unroll
;             for (int b = 0; b < 2; ++b)
; #pragma unroll
;                 for (int m = 0; m < 4; ++m)
; #pragma unroll
;                     for (int n = 0; n < 2; ++n) acc[a][b][m][n] = (f32x4){0.f, 0.f, 0.f, 0.f};
;         cur = nxt; cA = nA; cB = nB; ++ui;
.LBB0_269:
	s_ashr_i32 s57, s56, 31
	s_lshl_b64 s[8:9], s[56:57], 19
	s_add_u32 s58, s48, s8
	s_addc_u32 s59, s49, s9
	s_and_b64 s[8:9], s[38:39], exec
	s_cselect_b32 s1, s59, s65
	s_cselect_b32 s57, s58, s64
	s_ashr_i32 s31, s30, 31
	s_lshl_b64 s[8:9], s[30:31], 19
	s_add_u32 s60, s7, s8
	s_addc_u32 s61, s76, s9
	s_and_b64 s[8:9], s[38:39], exec
	s_cselect_b32 s31, s61, s67
	s_cselect_b32 s95, s60, s66
	s_add_u32 s64, s64, 0x40080
	s_addc_u32 s65, s65, 0
	s_add_u32 s96, s66, 0x100
	v_mov_b32_e32 v0, 0
	s_addc_u32 s8, s67, 0
	s_mov_b32 s9, -2
	v_mov_b32_e32 v1, v0
	v_mov_b64_e32 v[2:3], v[0:1]
	v_mov_b64_e32 v[4:5], v[0:1]
	v_mov_b64_e32 v[6:7], v[0:1]
	v_mov_b64_e32 v[8:9], v[0:1]
	v_mov_b64_e32 v[10:11], v[0:1]
	v_mov_b64_e32 v[12:13], v[0:1]
	v_mov_b64_e32 v[14:15], v[0:1]
	v_mov_b64_e32 v[16:17], v[0:1]
	v_mov_b64_e32 v[18:19], v[0:1]
	v_mov_b64_e32 v[20:21], v[0:1]
	v_mov_b64_e32 v[22:23], v[0:1]
	v_mov_b64_e32 v[24:25], v[0:1]
	v_mov_b64_e32 v[26:27], v[0:1]
	v_mov_b64_e32 v[28:29], v[0:1]
	v_mov_b64_e32 v[30:31], v[0:1]
	v_mov_b64_e32 v[32:33], v[0:1]
	v_mov_b64_e32 v[34:35], v[0:1]
	v_mov_b64_e32 v[36:37], v[0:1]
	v_mov_b64_e32 v[38:39], v[0:1]
	v_mov_b64_e32 v[40:41], v[0:1]
	v_mov_b64_e32 v[42:43], v[0:1]
	v_mov_b64_e32 v[44:45], v[0:1]
	v_mov_b64_e32 v[46:47], v[0:1]
	v_mov_b64_e32 v[48:49], v[0:1]
	v_mov_b64_e32 v[50:51], v[0:1]
	v_mov_b64_e32 v[52:53], v[0:1]
	v_mov_b64_e32 v[54:55], v[0:1]
	v_mov_b64_e32 v[56:57], v[0:1]
	v_mov_b64_e32 v[58:59], v[0:1]
	v_mov_b64_e32 v[60:61], v[0:1]
	v_mov_b64_e32 v[62:63], v[0:1]
	v_mov_b64_e32 v[64:65], v[0:1]
	v_mov_b64_e32 v[66:67], v[0:1]
	v_mov_b64_e32 v[68:69], v[0:1]
	v_mov_b64_e32 v[70:71], v[0:1]
	v_mov_b64_e32 v[72:73], v[0:1]
	v_mov_b64_e32 v[74:75], v[0:1]
	v_mov_b64_e32 v[76:77], v[0:1]
	v_mov_b64_e32 v[78:79], v[0:1]
	v_mov_b64_e32 v[80:81], v[0:1]
	v_mov_b64_e32 v[82:83], v[0:1]
	v_mov_b64_e32 v[84:85], v[0:1]
	v_mov_b64_e32 v[86:87], v[0:1]
	v_mov_b64_e32 v[88:89], v[0:1]
	v_mov_b64_e32 v[90:91], v[0:1]
	v_mov_b64_e32 v[92:93], v[0:1]
	v_mov_b64_e32 v[94:95], v[0:1]
	v_mov_b64_e32 v[96:97], v[0:1]
	v_mov_b64_e32 v[98:99], v[0:1]
	v_mov_b64_e32 v[100:101], v[0:1]
	v_mov_b64_e32 v[102:103], v[0:1]
	v_mov_b64_e32 v[104:105], v[0:1]
	v_mov_b64_e32 v[106:107], v[0:1]
	v_mov_b64_e32 v[108:109], v[0:1]
	v_mov_b64_e32 v[110:111], v[0:1]
	v_mov_b64_e32 v[112:113], v[0:1]
	v_mov_b64_e32 v[114:115], v[0:1]
	v_mov_b64_e32 v[116:117], v[0:1]
	v_mov_b64_e32 v[118:119], v[0:1]
	v_mov_b64_e32 v[120:121], v[0:1]
	v_mov_b64_e32 v[122:123], v[0:1]
	v_mov_b64_e32 v[124:125], v[0:1]
	v_mov_b64_e32 v[126:127], v[0:1]

; template <class Epi, class Sched, bool ALIGN_EPI = false, bool SP2 = false>
; __device__ __forceinline__ void gemm_phase(PG8_LAS unsigned char* lds, const Gemm g, const Sched& S, const Epi& E, const int tid) {
;     ...
;         const bool has_next = S.next(ui + 1, nxt);
;         const char* nA = has_next ? (const char*)g.A + (size_t)nxt.pm * tstep : cA; const char* nB = has_next ? (const char*)g.Bt + (size_t)nxt.pn * tstep : cB;
;         for (int t = 0; t < nt; t += 2) {
;             const bool last = (t == nt - 2);
;             const char* a1 = cA + (size_t)(t + 1) * kstep;
;             const char* a2 = last ? nA : cA + (size_t)(t + 2) * kstep; const char* b2 = last ? nB : cB + (size_t)(t + 2) * kstep;
;     ...
; #pragma unroll
;         for (int a = 0; a < 2; ++a)
; #pragma unroll
;             for (int b = 0; b < 2; ++b)
; #pragma unroll
;                 for (int m = 0; m < 4; ++m)
; #pragma unroll
;                     for (int n = 0; n < 2; ++n) acc[a][b][m][n] = (f32x4){0.f, 0.f, 0.f, 0.f};
;         cur = nxt; cA = nA; cB = nB; ++ui;
.LBB0_458:
	s_ashr_i32 s53, s52, 31
	s_lshl_b64 s[8:9], s[52:53], 19
	s_add_u32 s54, s46, s8
	s_addc_u32 s55, s47, s9
	s_and_b64 s[8:9], s[40:41], exec
	s_cselect_b32 s45, s55, s1
	s_cselect_b32 s50, s54, s0
	s_ashr_i32 s61, s60, 31
	s_lshl_b64 s[8:9], s[60:61], 19
	s_add_u32 s84, s17, s8
	s_addc_u32 s85, s16, s9
	s_and_b64 s[8:9], s[40:41], exec
	s_cselect_b32 s51, s85, s43
	s_cselect_b32 s53, s84, s42
	s_add_u32 s0, s0, 0x40080
	s_addc_u32 s1, s1, 0
	s_add_u32 s56, s42, 0x100
	v_mov_b32_e32 v0, 0
	s_addc_u32 s57, s43, 0
	s_mov_b32 s8, -2
	v_mov_b32_e32 v1, v0
	v_mov_b64_e32 v[2:3], v[0:1]
	v_mov_b64_e32 v[4:5], v[0:1]
	v_mov_b64_e32 v[6:7], v[0:1]
	v_mov_b64_e32 v[8:9], v[0:1]
	v_mov_b64_e32 v[10:11], v[0:1]
	v_mov_b64_e32 v[12:13], v[0:1]
	v_mov_b64_e32 v[14:15], v[0:1]
	v_mov_b64_e32 v[16:17], v[0:1]
	v_mov_b64_e32 v[18:19], v[0:1]
	v_mov_b64_e32 v[20:21], v[0:1]
	v_mov_b64_e32 v[22:23], v[0:1]
	v_mov_b64_e32 v[24:25], v[0:1]
	v_mov_b64_e32 v[26:27], v[0:1]
	v_mov_b64_e32 v[28:29], v[0:1]
	v_mov_b64_e32 v[30:31], v[0:1]
	v_mov_b64_e32 v[32:33], v[0:1]
	v_mov_b64_e32 v[34:35], v[0:1]
	v_mov_b64_e32 v[36:37], v[0:1]
	v_mov_b64_e32 v[38:39], v[0:1]
	v_mov_b64_e32 v[40:41], v[0:1]
	v_mov_b64_e32 v[42:43], v[0:1]
	v_mov_b64_e32 v[44:45], v[0:1]
	v_mov_b64_e32 v[46:47], v[0:1]
	v_mov_b64_e32 v[48:49], v[0:1]
	v_mov_b64_e32 v[50:51], v[0:1]
	v_mov_b64_e32 v[52:53], v[0:1]
	v_mov_b64_e32 v[54:55], v[0:1]
	v_mov_b64_e32 v[56:57], v[0:1]
	v_mov_b64_e32 v[58:59], v[0:1]
	v_mov_b64_e32 v[60:61], v[0:1]
	v_mov_b64_e32 v[62:63], v[0:1]
	v_mov_b64_e32 v[64:65], v[0:1]
	v_mov_b64_e32 v[66:67], v[0:1]
	v_mov_b64_e32 v[68:69], v[0:1]
	v_mov_b64_e32 v[70:71], v[0:1]
	v_mov_b64_e32 v[72:73], v[0:1]
	v_mov_b64_e32 v[74:75], v[0:1]
	v_mov_b64_e32 v[76:77], v[0:1]
	v_mov_b64_e32 v[78:79], v[0:1]
	v_mov_b64_e32 v[80:81], v[0:1]
	v_mov_b64_e32 v[82:83], v[0:1]
	v_mov_b64_e32 v[84:85], v[0:1]
	v_mov_b64_e32 v[86:87], v[0:1]
	v_mov_b64_e32 v[88:89], v[0:1]
	v_mov_b64_e32 v[90:91], v[0:1]
	v_mov_b64_e32 v[92:93], v[0:1]
	v_mov_b64_e32 v[94:95], v[0:1]
	v_mov_b64_e32 v[96:97], v[0:1]
	v_mov_b64_e32 v[98:99], v[0:1]
	v_mov_b64_e32 v[100:101], v[0:1]
	v_mov_b64_e32 v[102:103], v[0:1]
	v_mov_b64_e32 v[104:105], v[0:1]
	v_mov_b64_e32 v[106:107], v[0:1]
	v_mov_b64_e32 v[108:109], v[0:1]
	v_mov_b64_e32 v[110:111], v[0:1]
	v_mov_b64_e32 v[112:113], v[0:1]
	v_mov_b64_e32 v[114:115], v[0:1]
	v_mov_b64_e32 v[116:117], v[0:1]
	v_mov_b64_e32 v[118:119], v[0:1]
	v_mov_b64_e32 v[120:121], v[0:1]
	v_mov_b64_e32 v[122:123], v[0:1]
	v_mov_b64_e32 v[124:125], v[0:1]
	v_mov_b64_e32 v[126:127], v[0:1]
